# hand-written pipelined attend fast path for prompt items with 256 selected keys (global loads, counted vmcnt, ring-buffered K/V gathers)
# speedup vs baseline: 1.0307x; 1.0307x over previous
.LBB0_683:
	s_or_b64 exec, exec, s[0:1]
	s_waitcnt lgkmcnt(0)
	s_cmp_eq_u64 s[18:19], exec
	s_cbranch_scc0 .Lfa_skip
	v_readfirstlane_b32 s52, v223
	s_cmpk_eq_i32 s52, 0x100
	s_cbranch_scc0 .Lfa_skip
	v_readfirstlane_b32 s54, v211
	v_readfirstlane_b32 s57, v138
	v_readfirstlane_b32 s52, v130
	v_readlane_b32 s42, v251, 15
	v_readlane_b32 s43, v251, 16
	s_lshr_b32 s54, s54, 6
	s_add_i32 s57, s57, s54
	s_mul_i32 s55, s54, 0x4050
	s_mul_i32 s56, s54, 0x500
	s_add_i32 s56, s56, 0x20280
	s_lshl_b32 s52, s52, 20
	s_add_u32 s44, s42, s52
	s_addc_u32 s45, s43, 0
	s_add_u32 s46, s44, 0x22182200
	s_addc_u32 s47, s45, 0
	s_add_u32 s44, s44, 0x21982200
	s_addc_u32 s45, s45, 0
	s_lshl_b32 s52, s57, 10
	s_add_u32 s48, s42, s52
	s_addc_u32 s49, s43, 0
	s_add_u32 s50, s48, 0x1a580000
	s_addc_u32 s51, s49, 0
	s_add_u32 s48, s48, 0x6080000
	s_addc_u32 s49, s49, 0
	s_mov_b32 s70, 0x000f000f
	s_mov_b32 s71, 0x000f000f
	s_mov_b32 s58, 0x3e000000
	s_mov_b32 s59, 0x3e000000
	v_and_b32_e32 v202, 15, v219
	v_lshrrev_b32_e32 v223, 4, v219
	v_lshlrev_b32_e32 v194, 4, v223
	v_lshl_add_u32 v191, v202, 2, s56
	v_lshl_add_u32 v199, v202, 5, s55
	ds_read_b32 v126, v191 offset:0
	ds_read_b32 v127, v191 offset:64
	ds_read_b32 v128, v191 offset:128
	ds_read_b32 v129, v191 offset:192
	ds_read_b32 v130, v191 offset:256
	ds_read_b32 v131, v191 offset:320
	ds_read_b32 v132, v191 offset:384
	ds_read_b32 v133, v191 offset:448
	ds_read_b32 v134, v191 offset:512
	ds_read_b32 v135, v191 offset:576
	ds_read_b32 v136, v191 offset:640
	ds_read_b32 v137, v191 offset:704
	ds_read_b32 v138, v191 offset:768
	ds_read_b32 v139, v191 offset:832
	ds_read_b32 v140, v191 offset:896
	ds_read_b32 v141, v191 offset:960
	v_mov_b32_e32 v2, 0
	v_mov_b32_e32 v3, 0
	v_mov_b32_e32 v4, 0
	v_mov_b32_e32 v5, 0
	v_mov_b32_e32 v6, 0
	v_mov_b32_e32 v7, 0
	v_mov_b32_e32 v8, 0
	v_mov_b32_e32 v9, 0
	v_mov_b32_e32 v10, 0
	v_mov_b32_e32 v11, 0
	v_mov_b32_e32 v12, 0
	v_mov_b32_e32 v13, 0
	v_mov_b32_e32 v14, 0
	v_mov_b32_e32 v15, 0
	v_mov_b32_e32 v16, 0
	v_mov_b32_e32 v17, 0
	v_lshl_add_u32 v0, v202, 7, v194
	s_mov_b64 exec, s[70:71]
	global_load_dwordx4 v[2:5], v0, s[48:49] offset:0
	global_load_dwordx4 v[6:9], v0, s[48:49] offset:64
	global_load_dwordx4 v[10:13], v0, s[48:49] offset:512
	global_load_dwordx4 v[14:17], v0, s[48:49] offset:576
	s_mov_b64 exec, -1
	s_waitcnt lgkmcnt(11)
	v_lshl_add_u32 v126, v126, 8, v194
	global_load_dwordx4 v[18:21], v126, s[44:45] offset:0
	global_load_dwordx4 v[22:25], v126, s[44:45] offset:64
	global_load_dwordx4 v[26:29], v126, s[44:45] offset:128
	global_load_dwordx4 v[30:33], v126, s[44:45] offset:192
	v_lshl_add_u32 v127, v127, 8, v194
	global_load_dwordx4 v[34:37], v127, s[44:45] offset:0
	global_load_dwordx4 v[38:41], v127, s[44:45] offset:64
	global_load_dwordx4 v[42:45], v127, s[44:45] offset:128
	global_load_dwordx4 v[46:49], v127, s[44:45] offset:192
	v_lshl_add_u32 v128, v128, 8, v194
	global_load_dwordx4 v[50:53], v128, s[44:45] offset:0
	global_load_dwordx4 v[54:57], v128, s[44:45] offset:64
	global_load_dwordx4 v[58:61], v128, s[44:45] offset:128
	global_load_dwordx4 v[62:65], v128, s[44:45] offset:192
	v_lshl_add_u32 v129, v129, 8, v194
	global_load_dwordx4 v[94:97], v129, s[44:45] offset:0
	global_load_dwordx4 v[98:101], v129, s[44:45] offset:64
	global_load_dwordx4 v[102:105], v129, s[44:45] offset:128
	global_load_dwordx4 v[106:109], v129, s[44:45] offset:192
	v_lshl_add_u32 v130, v130, 8, v194
	global_load_dwordx4 v[110:113], v130, s[44:45] offset:0
	global_load_dwordx4 v[114:117], v130, s[44:45] offset:64
	global_load_dwordx4 v[118:121], v130, s[44:45] offset:128
	global_load_dwordx4 v[122:125], v130, s[44:45] offset:192
	s_waitcnt lgkmcnt(0)
	s_waitcnt vmcnt(16)
	v_mfma_f32_16x16x32_bf16 v[66:69], v[2:5], v[18:21], 0
	v_mfma_f32_16x16x32_bf16 v[70:73], v[10:13], v[26:29], 0
	v_mfma_f32_16x16x32_bf16 v[66:69], v[6:9], v[22:25], v[66:69]
	v_mfma_f32_16x16x32_bf16 v[70:73], v[14:17], v[30:33], v[70:73]
	v_lshl_add_u32 v131, v131, 8, v194
	global_load_dwordx4 v[18:21], v131, s[44:45] offset:0
	global_load_dwordx4 v[22:25], v131, s[44:45] offset:64
	global_load_dwordx4 v[26:29], v131, s[44:45] offset:128
	global_load_dwordx4 v[30:33], v131, s[44:45] offset:192
	s_nop 7
	s_waitcnt vmcnt(16)
	v_mfma_f32_16x16x32_bf16 v[226:229], v[2:5], v[34:37], 0
	v_mfma_f32_16x16x32_bf16 v[230:233], v[10:13], v[42:45], 0
	v_mfma_f32_16x16x32_bf16 v[226:229], v[6:9], v[38:41], v[226:229]
	v_mfma_f32_16x16x32_bf16 v[230:233], v[14:17], v[46:49], v[230:233]
	v_lshl_add_u32 v132, v132, 8, v194
	global_load_dwordx4 v[34:37], v132, s[44:45] offset:0
	global_load_dwordx4 v[38:41], v132, s[44:45] offset:64
	global_load_dwordx4 v[42:45], v132, s[44:45] offset:128
	global_load_dwordx4 v[46:49], v132, s[44:45] offset:192
	v_pk_mul_f32 v[66:67], v[66:67], s[58:59] op_sel_hi:[1,0]
	v_pk_mul_f32 v[68:69], v[68:69], s[58:59] op_sel_hi:[1,0]
	v_pk_mul_f32 v[70:71], v[70:71], s[58:59] op_sel_hi:[1,0]
	v_pk_mul_f32 v[72:73], v[72:73], s[58:59] op_sel_hi:[1,0]
	s_mov_b64 exec, 0xffff
	ds_write_b128 v199, v[66:69] offset:0
	ds_write_b128 v199, v[70:73] offset:16
	s_mov_b64 exec, -1
	s_waitcnt vmcnt(16)
	v_mfma_f32_16x16x32_bf16 v[66:69], v[2:5], v[50:53], 0
	v_mfma_f32_16x16x32_bf16 v[70:73], v[10:13], v[58:61], 0
	v_mfma_f32_16x16x32_bf16 v[66:69], v[6:9], v[54:57], v[66:69]
	v_mfma_f32_16x16x32_bf16 v[70:73], v[14:17], v[62:65], v[70:73]
	v_lshl_add_u32 v133, v133, 8, v194
	global_load_dwordx4 v[50:53], v133, s[44:45] offset:0
	global_load_dwordx4 v[54:57], v133, s[44:45] offset:64
	global_load_dwordx4 v[58:61], v133, s[44:45] offset:128
	global_load_dwordx4 v[62:65], v133, s[44:45] offset:192
	v_pk_mul_f32 v[226:227], v[226:227], s[58:59] op_sel_hi:[1,0]
	v_pk_mul_f32 v[228:229], v[228:229], s[58:59] op_sel_hi:[1,0]
	v_pk_mul_f32 v[230:231], v[230:231], s[58:59] op_sel_hi:[1,0]
	v_pk_mul_f32 v[232:233], v[232:233], s[58:59] op_sel_hi:[1,0]
	s_mov_b64 exec, 0xffff
	ds_write_b128 v199, v[226:229] offset:512
	ds_write_b128 v199, v[230:233] offset:528
	s_mov_b64 exec, -1
	s_waitcnt vmcnt(16)
	v_mfma_f32_16x16x32_bf16 v[226:229], v[2:5], v[94:97], 0
	v_mfma_f32_16x16x32_bf16 v[230:233], v[10:13], v[102:105], 0
	v_mfma_f32_16x16x32_bf16 v[226:229], v[6:9], v[98:101], v[226:229]
	v_mfma_f32_16x16x32_bf16 v[230:233], v[14:17], v[106:109], v[230:233]
	v_lshl_add_u32 v134, v134, 8, v194
	global_load_dwordx4 v[94:97], v134, s[44:45] offset:0
	global_load_dwordx4 v[98:101], v134, s[44:45] offset:64
	global_load_dwordx4 v[102:105], v134, s[44:45] offset:128
	global_load_dwordx4 v[106:109], v134, s[44:45] offset:192
	v_pk_mul_f32 v[66:67], v[66:67], s[58:59] op_sel_hi:[1,0]
	v_pk_mul_f32 v[68:69], v[68:69], s[58:59] op_sel_hi:[1,0]
	v_pk_mul_f32 v[70:71], v[70:71], s[58:59] op_sel_hi:[1,0]
	v_pk_mul_f32 v[72:73], v[72:73], s[58:59] op_sel_hi:[1,0]
	s_mov_b64 exec, 0xffff
	ds_write_b128 v199, v[66:69] offset:1056
	ds_write_b128 v199, v[70:73] offset:1072
	s_mov_b64 exec, -1
	s_waitcnt vmcnt(16)
	v_mfma_f32_16x16x32_bf16 v[66:69], v[2:5], v[110:113], 0
	v_mfma_f32_16x16x32_bf16 v[70:73], v[10:13], v[118:121], 0
	v_mfma_f32_16x16x32_bf16 v[66:69], v[6:9], v[114:117], v[66:69]
	v_mfma_f32_16x16x32_bf16 v[70:73], v[14:17], v[122:125], v[70:73]
	v_lshl_add_u32 v135, v135, 8, v194
	global_load_dwordx4 v[110:113], v135, s[44:45] offset:0
	global_load_dwordx4 v[114:117], v135, s[44:45] offset:64
	global_load_dwordx4 v[118:121], v135, s[44:45] offset:128
	global_load_dwordx4 v[122:125], v135, s[44:45] offset:192
	v_pk_mul_f32 v[226:227], v[226:227], s[58:59] op_sel_hi:[1,0]
	v_pk_mul_f32 v[228:229], v[228:229], s[58:59] op_sel_hi:[1,0]
	v_pk_mul_f32 v[230:231], v[230:231], s[58:59] op_sel_hi:[1,0]
	v_pk_mul_f32 v[232:233], v[232:233], s[58:59] op_sel_hi:[1,0]
	s_mov_b64 exec, 0xffff
	ds_write_b128 v199, v[226:229] offset:1568
	ds_write_b128 v199, v[230:233] offset:1584
	s_mov_b64 exec, -1
	s_waitcnt vmcnt(16)
	v_mfma_f32_16x16x32_bf16 v[226:229], v[2:5], v[18:21], 0
	v_mfma_f32_16x16x32_bf16 v[230:233], v[10:13], v[26:29], 0
	v_mfma_f32_16x16x32_bf16 v[226:229], v[6:9], v[22:25], v[226:229]
	v_mfma_f32_16x16x32_bf16 v[230:233], v[14:17], v[30:33], v[230:233]
	v_lshl_add_u32 v136, v136, 8, v194
	global_load_dwordx4 v[18:21], v136, s[44:45] offset:0
	global_load_dwordx4 v[22:25], v136, s[44:45] offset:64
	global_load_dwordx4 v[26:29], v136, s[44:45] offset:128
	global_load_dwordx4 v[30:33], v136, s[44:45] offset:192
	v_pk_mul_f32 v[66:67], v[66:67], s[58:59] op_sel_hi:[1,0]
	v_pk_mul_f32 v[68:69], v[68:69], s[58:59] op_sel_hi:[1,0]
	v_pk_mul_f32 v[70:71], v[70:71], s[58:59] op_sel_hi:[1,0]
	v_pk_mul_f32 v[72:73], v[72:73], s[58:59] op_sel_hi:[1,0]
	s_mov_b64 exec, 0xffff
	ds_write_b128 v199, v[66:69] offset:2112
	ds_write_b128 v199, v[70:73] offset:2128
	s_mov_b64 exec, -1
	s_waitcnt vmcnt(16)
	v_mfma_f32_16x16x32_bf16 v[66:69], v[2:5], v[34:37], 0
	v_mfma_f32_16x16x32_bf16 v[70:73], v[10:13], v[42:45], 0
	v_mfma_f32_16x16x32_bf16 v[66:69], v[6:9], v[38:41], v[66:69]
	v_mfma_f32_16x16x32_bf16 v[70:73], v[14:17], v[46:49], v[70:73]
	v_lshl_add_u32 v137, v137, 8, v194
	global_load_dwordx4 v[34:37], v137, s[44:45] offset:0
	global_load_dwordx4 v[38:41], v137, s[44:45] offset:64
	global_load_dwordx4 v[42:45], v137, s[44:45] offset:128
	global_load_dwordx4 v[46:49], v137, s[44:45] offset:192
	v_pk_mul_f32 v[226:227], v[226:227], s[58:59] op_sel_hi:[1,0]
	v_pk_mul_f32 v[228:229], v[228:229], s[58:59] op_sel_hi:[1,0]
	v_pk_mul_f32 v[230:231], v[230:231], s[58:59] op_sel_hi:[1,0]
	v_pk_mul_f32 v[232:233], v[232:233], s[58:59] op_sel_hi:[1,0]
	s_mov_b64 exec, 0xffff
	ds_write_b128 v199, v[226:229] offset:2624
	ds_write_b128 v199, v[230:233] offset:2640
	s_mov_b64 exec, -1
	s_waitcnt vmcnt(16)
	v_mfma_f32_16x16x32_bf16 v[226:229], v[2:5], v[50:53], 0
	v_mfma_f32_16x16x32_bf16 v[230:233], v[10:13], v[58:61], 0
	v_mfma_f32_16x16x32_bf16 v[226:229], v[6:9], v[54:57], v[226:229]
	v_mfma_f32_16x16x32_bf16 v[230:233], v[14:17], v[62:65], v[230:233]
	v_lshl_add_u32 v138, v138, 8, v194
	global_load_dwordx4 v[50:53], v138, s[44:45] offset:0
	global_load_dwordx4 v[54:57], v138, s[44:45] offset:64
	global_load_dwordx4 v[58:61], v138, s[44:45] offset:128
	global_load_dwordx4 v[62:65], v138, s[44:45] offset:192
	v_pk_mul_f32 v[66:67], v[66:67], s[58:59] op_sel_hi:[1,0]
	v_pk_mul_f32 v[68:69], v[68:69], s[58:59] op_sel_hi:[1,0]
	v_pk_mul_f32 v[70:71], v[70:71], s[58:59] op_sel_hi:[1,0]
	v_pk_mul_f32 v[72:73], v[72:73], s[58:59] op_sel_hi:[1,0]
	s_mov_b64 exec, 0xffff
	ds_write_b128 v199, v[66:69] offset:3168
	ds_write_b128 v199, v[70:73] offset:3184
	s_mov_b64 exec, -1
	s_waitcnt vmcnt(16)
	v_mfma_f32_16x16x32_bf16 v[66:69], v[2:5], v[94:97], 0
	v_mfma_f32_16x16x32_bf16 v[70:73], v[10:13], v[102:105], 0
	v_mfma_f32_16x16x32_bf16 v[66:69], v[6:9], v[98:101], v[66:69]
	v_mfma_f32_16x16x32_bf16 v[70:73], v[14:17], v[106:109], v[70:73]
	v_lshl_add_u32 v139, v139, 8, v194
	global_load_dwordx4 v[94:97], v139, s[44:45] offset:0
	global_load_dwordx4 v[98:101], v139, s[44:45] offset:64
	global_load_dwordx4 v[102:105], v139, s[44:45] offset:128
	global_load_dwordx4 v[106:109], v139, s[44:45] offset:192
	v_pk_mul_f32 v[226:227], v[226:227], s[58:59] op_sel_hi:[1,0]
	v_pk_mul_f32 v[228:229], v[228:229], s[58:59] op_sel_hi:[1,0]
	v_pk_mul_f32 v[230:231], v[230:231], s[58:59] op_sel_hi:[1,0]
	v_pk_mul_f32 v[232:233], v[232:233], s[58:59] op_sel_hi:[1,0]
	s_mov_b64 exec, 0xffff
	ds_write_b128 v199, v[226:229] offset:3680
	ds_write_b128 v199, v[230:233] offset:3696
	s_mov_b64 exec, -1
	s_waitcnt vmcnt(16)
	v_mfma_f32_16x16x32_bf16 v[226:229], v[2:5], v[110:113], 0
	v_mfma_f32_16x16x32_bf16 v[230:233], v[10:13], v[118:121], 0
	v_mfma_f32_16x16x32_bf16 v[226:229], v[6:9], v[114:117], v[226:229]
	v_mfma_f32_16x16x32_bf16 v[230:233], v[14:17], v[122:125], v[230:233]
	v_lshl_add_u32 v140, v140, 8, v194
	global_load_dwordx4 v[110:113], v140, s[44:45] offset:0
	global_load_dwordx4 v[114:117], v140, s[44:45] offset:64
	global_load_dwordx4 v[118:121], v140, s[44:45] offset:128
	global_load_dwordx4 v[122:125], v140, s[44:45] offset:192
	v_pk_mul_f32 v[66:67], v[66:67], s[58:59] op_sel_hi:[1,0]
	v_pk_mul_f32 v[68:69], v[68:69], s[58:59] op_sel_hi:[1,0]
	v_pk_mul_f32 v[70:71], v[70:71], s[58:59] op_sel_hi:[1,0]
	v_pk_mul_f32 v[72:73], v[72:73], s[58:59] op_sel_hi:[1,0]
	s_mov_b64 exec, 0xffff
	ds_write_b128 v199, v[66:69] offset:4224
	ds_write_b128 v199, v[70:73] offset:4240
	s_mov_b64 exec, -1
	s_waitcnt vmcnt(16)
	v_mfma_f32_16x16x32_bf16 v[66:69], v[2:5], v[18:21], 0
	v_mfma_f32_16x16x32_bf16 v[70:73], v[10:13], v[26:29], 0
	v_mfma_f32_16x16x32_bf16 v[66:69], v[6:9], v[22:25], v[66:69]
	v_mfma_f32_16x16x32_bf16 v[70:73], v[14:17], v[30:33], v[70:73]
	v_lshl_add_u32 v141, v141, 8, v194
	global_load_dwordx4 v[18:21], v141, s[44:45] offset:0
	global_load_dwordx4 v[22:25], v141, s[44:45] offset:64
	global_load_dwordx4 v[26:29], v141, s[44:45] offset:128
	global_load_dwordx4 v[30:33], v141, s[44:45] offset:192
	v_pk_mul_f32 v[226:227], v[226:227], s[58:59] op_sel_hi:[1,0]
	v_pk_mul_f32 v[228:229], v[228:229], s[58:59] op_sel_hi:[1,0]
	v_pk_mul_f32 v[230:231], v[230:231], s[58:59] op_sel_hi:[1,0]
	v_pk_mul_f32 v[232:233], v[232:233], s[58:59] op_sel_hi:[1,0]
	s_mov_b64 exec, 0xffff
	ds_write_b128 v199, v[226:229] offset:4736
	ds_write_b128 v199, v[230:233] offset:4752
	s_mov_b64 exec, -1
	s_waitcnt vmcnt(16)
	v_mfma_f32_16x16x32_bf16 v[226:229], v[2:5], v[34:37], 0
	v_mfma_f32_16x16x32_bf16 v[230:233], v[10:13], v[42:45], 0
	v_mfma_f32_16x16x32_bf16 v[226:229], v[6:9], v[38:41], v[226:229]
	v_mfma_f32_16x16x32_bf16 v[230:233], v[14:17], v[46:49], v[230:233]
	v_pk_mul_f32 v[66:67], v[66:67], s[58:59] op_sel_hi:[1,0]
	v_pk_mul_f32 v[68:69], v[68:69], s[58:59] op_sel_hi:[1,0]
	v_pk_mul_f32 v[70:71], v[70:71], s[58:59] op_sel_hi:[1,0]
	v_pk_mul_f32 v[72:73], v[72:73], s[58:59] op_sel_hi:[1,0]
	s_mov_b64 exec, 0xffff
	ds_write_b128 v199, v[66:69] offset:5280
	ds_write_b128 v199, v[70:73] offset:5296
	s_mov_b64 exec, -1
	s_waitcnt vmcnt(12)
	v_mfma_f32_16x16x32_bf16 v[66:69], v[2:5], v[50:53], 0
	v_mfma_f32_16x16x32_bf16 v[70:73], v[10:13], v[58:61], 0
	v_mfma_f32_16x16x32_bf16 v[66:69], v[6:9], v[54:57], v[66:69]
	v_mfma_f32_16x16x32_bf16 v[70:73], v[14:17], v[62:65], v[70:73]
	v_pk_mul_f32 v[226:227], v[226:227], s[58:59] op_sel_hi:[1,0]
	v_pk_mul_f32 v[228:229], v[228:229], s[58:59] op_sel_hi:[1,0]
	v_pk_mul_f32 v[230:231], v[230:231], s[58:59] op_sel_hi:[1,0]
	v_pk_mul_f32 v[232:233], v[232:233], s[58:59] op_sel_hi:[1,0]
	s_mov_b64 exec, 0xffff
	ds_write_b128 v199, v[226:229] offset:5792
	ds_write_b128 v199, v[230:233] offset:5808
	s_mov_b64 exec, -1
	s_waitcnt vmcnt(8)
	v_mfma_f32_16x16x32_bf16 v[226:229], v[2:5], v[94:97], 0
	v_mfma_f32_16x16x32_bf16 v[230:233], v[10:13], v[102:105], 0
	v_mfma_f32_16x16x32_bf16 v[226:229], v[6:9], v[98:101], v[226:229]
	v_mfma_f32_16x16x32_bf16 v[230:233], v[14:17], v[106:109], v[230:233]
	v_pk_mul_f32 v[66:67], v[66:67], s[58:59] op_sel_hi:[1,0]
	v_pk_mul_f32 v[68:69], v[68:69], s[58:59] op_sel_hi:[1,0]
	v_pk_mul_f32 v[70:71], v[70:71], s[58:59] op_sel_hi:[1,0]
	v_pk_mul_f32 v[72:73], v[72:73], s[58:59] op_sel_hi:[1,0]
	s_mov_b64 exec, 0xffff
	ds_write_b128 v199, v[66:69] offset:6336
	ds_write_b128 v199, v[70:73] offset:6352
	s_mov_b64 exec, -1
	s_waitcnt vmcnt(4)
	v_mfma_f32_16x16x32_bf16 v[66:69], v[2:5], v[110:113], 0
	v_mfma_f32_16x16x32_bf16 v[70:73], v[10:13], v[118:121], 0
	v_mfma_f32_16x16x32_bf16 v[66:69], v[6:9], v[114:117], v[66:69]
	v_mfma_f32_16x16x32_bf16 v[70:73], v[14:17], v[122:125], v[70:73]
	v_pk_mul_f32 v[226:227], v[226:227], s[58:59] op_sel_hi:[1,0]
	v_pk_mul_f32 v[228:229], v[228:229], s[58:59] op_sel_hi:[1,0]
	v_pk_mul_f32 v[230:231], v[230:231], s[58:59] op_sel_hi:[1,0]
	v_pk_mul_f32 v[232:233], v[232:233], s[58:59] op_sel_hi:[1,0]
	s_mov_b64 exec, 0xffff
	ds_write_b128 v199, v[226:229] offset:6848
	ds_write_b128 v199, v[230:233] offset:6864
	s_mov_b64 exec, -1
	s_waitcnt vmcnt(0)
	v_mfma_f32_16x16x32_bf16 v[226:229], v[2:5], v[18:21], 0
	v_mfma_f32_16x16x32_bf16 v[230:233], v[10:13], v[26:29], 0
	v_mfma_f32_16x16x32_bf16 v[226:229], v[6:9], v[22:25], v[226:229]
	v_mfma_f32_16x16x32_bf16 v[230:233], v[14:17], v[30:33], v[230:233]
	v_pk_mul_f32 v[66:67], v[66:67], s[58:59] op_sel_hi:[1,0]
	v_pk_mul_f32 v[68:69], v[68:69], s[58:59] op_sel_hi:[1,0]
	v_pk_mul_f32 v[70:71], v[70:71], s[58:59] op_sel_hi:[1,0]
	v_pk_mul_f32 v[72:73], v[72:73], s[58:59] op_sel_hi:[1,0]
	s_mov_b64 exec, 0xffff
	ds_write_b128 v199, v[66:69] offset:7392
	ds_write_b128 v199, v[70:73] offset:7408
	s_mov_b64 exec, -1
	s_nop 7
	s_nop 1
	v_pk_mul_f32 v[226:227], v[226:227], s[58:59] op_sel_hi:[1,0]
	v_pk_mul_f32 v[228:229], v[228:229], s[58:59] op_sel_hi:[1,0]
	v_pk_mul_f32 v[230:231], v[230:231], s[58:59] op_sel_hi:[1,0]
	v_pk_mul_f32 v[232:233], v[232:233], s[58:59] op_sel_hi:[1,0]
	s_mov_b64 exec, 0xffff
	ds_write_b128 v199, v[226:229] offset:7904
	ds_write_b128 v199, v[230:233] offset:7920
	s_mov_b64 exec, -1
	v_lshl_add_u32 v191, v223, 2, s56
	v_lshlrev_b32_e32 v194, 4, v202
	ds_read2_b32 v[126:127], v191 offset0:0 offset1:4
	ds_read2_b32 v[128:129], v191 offset0:8 offset1:12
	ds_read2_b32 v[130:131], v191 offset0:16 offset1:20
	ds_read2_b32 v[132:133], v191 offset0:24 offset1:28
	s_waitcnt lgkmcnt(0)
	v_lshl_add_u32 v126, v126, 8, v194
	v_lshl_add_u32 v127, v127, 8, v194
	v_lshl_add_u32 v128, v128, 8, v194
	v_lshl_add_u32 v129, v129, 8, v194
	v_lshl_add_u32 v130, v130, 8, v194
	v_lshl_add_u32 v131, v131, 8, v194
	v_lshl_add_u32 v132, v132, 8, v194
	v_lshl_add_u32 v133, v133, 8, v194
	global_load_dwordx4 v[18:21], v126, s[46:47]
	global_load_dwordx4 v[22:25], v127, s[46:47]
	global_load_dwordx4 v[26:29], v128, s[46:47]
	global_load_dwordx4 v[30:33], v129, s[46:47]
	global_load_dwordx4 v[34:37], v130, s[46:47]
	global_load_dwordx4 v[38:41], v131, s[46:47]
	global_load_dwordx4 v[42:45], v132, s[46:47]
	global_load_dwordx4 v[46:49], v133, s[46:47]
	ds_read2_b32 v[126:127], v191 offset0:32 offset1:36
	ds_read2_b32 v[128:129], v191 offset0:40 offset1:44
	ds_read2_b32 v[130:131], v191 offset0:48 offset1:52
	ds_read2_b32 v[132:133], v191 offset0:56 offset1:60
	s_waitcnt lgkmcnt(0)
	v_lshl_add_u32 v126, v126, 8, v194
	v_lshl_add_u32 v127, v127, 8, v194
	v_lshl_add_u32 v128, v128, 8, v194
	v_lshl_add_u32 v129, v129, 8, v194
	v_lshl_add_u32 v130, v130, 8, v194
	v_lshl_add_u32 v131, v131, 8, v194
	v_lshl_add_u32 v132, v132, 8, v194
	v_lshl_add_u32 v133, v133, 8, v194
	global_load_dwordx4 v[94:97], v126, s[46:47]
	global_load_dwordx4 v[98:101], v127, s[46:47]
	global_load_dwordx4 v[102:105], v128, s[46:47]
	global_load_dwordx4 v[106:109], v129, s[46:47]
	global_load_dwordx4 v[110:113], v130, s[46:47]
	global_load_dwordx4 v[114:117], v131, s[46:47]
	global_load_dwordx4 v[118:121], v132, s[46:47]
	global_load_dwordx4 v[122:125], v133, s[46:47]
	v_and_b32_e32 v142, 7, v219
	v_lshrrev_b32_e32 v143, 3, v219
	v_mul_u32_u24_e32 v144, 0x420, v143
	v_lshl_add_u32 v144, v142, 2, v144
	v_add_u32_e32 v144, s55, v144
	ds_read2_b32 v[50:51], v144 offset0:0 offset1:8
	ds_read2_b32 v[52:53], v144 offset0:16 offset1:24
	ds_read2_b32 v[54:55], v144 offset0:32 offset1:40
	ds_read2_b32 v[56:57], v144 offset0:48 offset1:56
	ds_read2_b32 v[58:59], v144 offset0:64 offset1:72
	ds_read2_b32 v[60:61], v144 offset0:80 offset1:88
	ds_read2_b32 v[62:63], v144 offset0:96 offset1:104
	ds_read2_b32 v[64:65], v144 offset0:112 offset1:120
	ds_read2_b32 v[2:3], v144 offset0:128 offset1:136
	ds_read2_b32 v[4:5], v144 offset0:144 offset1:152
	ds_read2_b32 v[6:7], v144 offset0:160 offset1:168
	ds_read2_b32 v[8:9], v144 offset0:176 offset1:184
	ds_read2_b32 v[10:11], v144 offset0:192 offset1:200
	ds_read2_b32 v[12:13], v144 offset0:208 offset1:216
	ds_read2_b32 v[14:15], v144 offset0:224 offset1:232
	ds_read2_b32 v[16:17], v144 offset0:240 offset1:248
	s_waitcnt lgkmcnt(0)
	v_max3_f32 v145, v50, v51, v52
	v_max3_f32 v145, v145, v53, v54
	v_max3_f32 v145, v145, v55, v56
	v_max3_f32 v145, v145, v57, v58
	v_max3_f32 v145, v145, v59, v60
	v_max3_f32 v145, v145, v61, v62
	v_max3_f32 v145, v145, v63, v64
	v_max3_f32 v145, v145, v65, v2
	v_max3_f32 v145, v145, v3, v4
	v_max3_f32 v145, v145, v5, v6
	v_max3_f32 v145, v145, v7, v8
	v_max3_f32 v145, v145, v9, v10
	v_max3_f32 v145, v145, v11, v12
	v_max3_f32 v145, v145, v13, v14
	v_max3_f32 v145, v145, v15, v16
	v_max_f32_e32 v145, v145, v17
	s_nop 1
	v_mov_b32_dpp v0, v145 row_ror:8 row_mask:0xf bank_mask:0xf
	s_nop 1
	v_max_f32_e32 v145, v145, v0
	v_mov_b32_e32 v0, v145
	s_nop 1
	v_permlane16_swap_b32_e32 v145, v0
	s_nop 1
	v_max_f32_e32 v145, v145, v0
	v_mov_b32_e32 v0, v145
	s_nop 1
	v_permlane32_swap_b32_e32 v145, v0
	s_nop 1
	v_max_f32_e32 v145, v145, v0
	v_sub_f32_e32 v50, v50, v145
	v_sub_f32_e32 v51, v51, v145
	v_sub_f32_e32 v52, v52, v145
	v_sub_f32_e32 v53, v53, v145
	v_sub_f32_e32 v54, v54, v145
	v_sub_f32_e32 v55, v55, v145
	v_sub_f32_e32 v56, v56, v145
	v_sub_f32_e32 v57, v57, v145
	v_sub_f32_e32 v58, v58, v145
	v_sub_f32_e32 v59, v59, v145
	v_sub_f32_e32 v60, v60, v145
	v_sub_f32_e32 v61, v61, v145
	v_sub_f32_e32 v62, v62, v145
	v_sub_f32_e32 v63, v63, v145
	v_sub_f32_e32 v64, v64, v145
	v_sub_f32_e32 v65, v65, v145
	v_sub_f32_e32 v2, v2, v145
	v_sub_f32_e32 v3, v3, v145
	v_sub_f32_e32 v4, v4, v145
	v_sub_f32_e32 v5, v5, v145
	v_sub_f32_e32 v6, v6, v145
	v_sub_f32_e32 v7, v7, v145
	v_sub_f32_e32 v8, v8, v145
	v_sub_f32_e32 v9, v9, v145
	v_sub_f32_e32 v10, v10, v145
	v_sub_f32_e32 v11, v11, v145
	v_sub_f32_e32 v12, v12, v145
	v_sub_f32_e32 v13, v13, v145
	v_sub_f32_e32 v14, v14, v145
	v_sub_f32_e32 v15, v15, v145
	v_sub_f32_e32 v16, v16, v145
	v_sub_f32_e32 v17, v17, v145
	v_mul_f32_e32 v50, 0x3fb8aa3b, v50
	v_mul_f32_e32 v51, 0x3fb8aa3b, v51
	v_mul_f32_e32 v52, 0x3fb8aa3b, v52
	v_mul_f32_e32 v53, 0x3fb8aa3b, v53
	v_mul_f32_e32 v54, 0x3fb8aa3b, v54
	v_mul_f32_e32 v55, 0x3fb8aa3b, v55
	v_mul_f32_e32 v56, 0x3fb8aa3b, v56
	v_mul_f32_e32 v57, 0x3fb8aa3b, v57
	v_mul_f32_e32 v58, 0x3fb8aa3b, v58
	v_mul_f32_e32 v59, 0x3fb8aa3b, v59
	v_mul_f32_e32 v60, 0x3fb8aa3b, v60
	v_mul_f32_e32 v61, 0x3fb8aa3b, v61
	v_mul_f32_e32 v62, 0x3fb8aa3b, v62
	v_mul_f32_e32 v63, 0x3fb8aa3b, v63
	v_mul_f32_e32 v64, 0x3fb8aa3b, v64
	v_mul_f32_e32 v65, 0x3fb8aa3b, v65
	v_mul_f32_e32 v2, 0x3fb8aa3b, v2
	v_mul_f32_e32 v3, 0x3fb8aa3b, v3
	v_mul_f32_e32 v4, 0x3fb8aa3b, v4
	v_mul_f32_e32 v5, 0x3fb8aa3b, v5
	v_mul_f32_e32 v6, 0x3fb8aa3b, v6
	v_mul_f32_e32 v7, 0x3fb8aa3b, v7
	v_mul_f32_e32 v8, 0x3fb8aa3b, v8
	v_mul_f32_e32 v9, 0x3fb8aa3b, v9
	v_mul_f32_e32 v10, 0x3fb8aa3b, v10
	v_mul_f32_e32 v11, 0x3fb8aa3b, v11
	v_mul_f32_e32 v12, 0x3fb8aa3b, v12
	v_mul_f32_e32 v13, 0x3fb8aa3b, v13
	v_mul_f32_e32 v14, 0x3fb8aa3b, v14
	v_mul_f32_e32 v15, 0x3fb8aa3b, v15
	v_mul_f32_e32 v16, 0x3fb8aa3b, v16
	v_mul_f32_e32 v17, 0x3fb8aa3b, v17
	v_exp_f32_e32 v50, v50
	v_exp_f32_e32 v51, v51
	v_exp_f32_e32 v52, v52
	v_exp_f32_e32 v53, v53
	v_exp_f32_e32 v54, v54
	v_exp_f32_e32 v55, v55
	v_exp_f32_e32 v56, v56
	v_exp_f32_e32 v57, v57
	v_exp_f32_e32 v58, v58
	v_exp_f32_e32 v59, v59
	v_exp_f32_e32 v60, v60
	v_exp_f32_e32 v61, v61
	v_exp_f32_e32 v62, v62
	v_exp_f32_e32 v63, v63
	v_exp_f32_e32 v64, v64
	v_exp_f32_e32 v65, v65
	v_exp_f32_e32 v2, v2
	v_exp_f32_e32 v3, v3
	v_exp_f32_e32 v4, v4
	v_exp_f32_e32 v5, v5
	v_exp_f32_e32 v6, v6
	v_exp_f32_e32 v7, v7
	v_exp_f32_e32 v8, v8
	v_exp_f32_e32 v9, v9
	v_exp_f32_e32 v10, v10
	v_exp_f32_e32 v11, v11
	v_exp_f32_e32 v12, v12
	v_exp_f32_e32 v13, v13
	v_exp_f32_e32 v14, v14
	v_exp_f32_e32 v15, v15
	v_exp_f32_e32 v16, v16
	v_exp_f32_e32 v17, v17
	s_nop 0
	v_add_f32_e32 v145, v50, v51
	v_add_f32_e32 v145, v145, v52
	v_add_f32_e32 v145, v145, v53
	v_add_f32_e32 v145, v145, v54
	v_add_f32_e32 v145, v145, v55
	v_add_f32_e32 v145, v145, v56
	v_add_f32_e32 v145, v145, v57
	v_add_f32_e32 v145, v145, v58
	v_add_f32_e32 v145, v145, v59
	v_add_f32_e32 v145, v145, v60
	v_add_f32_e32 v145, v145, v61
	v_add_f32_e32 v145, v145, v62
	v_add_f32_e32 v145, v145, v63
	v_add_f32_e32 v145, v145, v64
	v_add_f32_e32 v145, v145, v65
	v_add_f32_e32 v145, v145, v2
	v_add_f32_e32 v145, v145, v3
	v_add_f32_e32 v145, v145, v4
	v_add_f32_e32 v145, v145, v5
	v_add_f32_e32 v145, v145, v6
	v_add_f32_e32 v145, v145, v7
	v_add_f32_e32 v145, v145, v8
	v_add_f32_e32 v145, v145, v9
	v_add_f32_e32 v145, v145, v10
	v_add_f32_e32 v145, v145, v11
	v_add_f32_e32 v145, v145, v12
	v_add_f32_e32 v145, v145, v13
	v_add_f32_e32 v145, v145, v14
	v_add_f32_e32 v145, v145, v15
	v_add_f32_e32 v145, v145, v16
	v_add_f32_e32 v145, v145, v17
	v_cvt_pk_bf16_f32 v66, v50, v51
	v_cvt_pk_bf16_f32 v67, v52, v53
	v_cvt_pk_bf16_f32 v68, v54, v55
	v_cvt_pk_bf16_f32 v69, v56, v57
	v_cvt_pk_bf16_f32 v70, v58, v59
	v_cvt_pk_bf16_f32 v71, v60, v61
	v_cvt_pk_bf16_f32 v72, v62, v63
	v_cvt_pk_bf16_f32 v73, v64, v65
	v_cvt_pk_bf16_f32 v226, v2, v3
	v_cvt_pk_bf16_f32 v227, v4, v5
	v_cvt_pk_bf16_f32 v228, v6, v7
	v_cvt_pk_bf16_f32 v229, v8, v9
	v_cvt_pk_bf16_f32 v230, v10, v11
	v_cvt_pk_bf16_f32 v231, v12, v13
	v_cvt_pk_bf16_f32 v232, v14, v15
	v_cvt_pk_bf16_f32 v233, v16, v17
	v_mul_u32_u24_e32 v144, 0x210, v142
	v_lshl_add_u32 v144, v143, 6, v144
	v_add_u32_e32 v144, s55, v144
	ds_write_b128 v144, v[66:69] offset:9216
	ds_write_b128 v144, v[70:73] offset:9232
	ds_write_b128 v144, v[226:229] offset:9248
	ds_write_b128 v144, v[230:233] offset:9264
	s_nop 1
	v_mov_b32_dpp v0, v145 row_ror:8 row_mask:0xf bank_mask:0xf
	s_nop 1
	v_add_f32_e32 v145, v145, v0
	v_mov_b32_e32 v0, v145
	s_nop 1
	v_permlane16_swap_b32_e32 v145, v0
	s_nop 1
	v_add_f32_e32 v145, v145, v0
	v_mov_b32_e32 v0, v145
	s_nop 1
	v_permlane32_swap_b32_e32 v145, v0
	s_nop 1
	v_add_f32_e32 v145, v145, v0
	v_rcp_f32_e32 v145, v145
	s_nop 1
	v_readlane_b32 s62, v145, 0
	v_readlane_b32 s63, v145, 1
	v_readlane_b32 s64, v145, 2
	v_readlane_b32 s65, v145, 3
	v_readlane_b32 s66, v145, 4
	v_readlane_b32 s67, v145, 5
	v_readlane_b32 s68, v145, 6
	v_readlane_b32 s69, v145, 7
	v_mov_b32_e32 v50, 0
	v_mov_b32_e32 v51, 0
	v_mov_b32_e32 v52, 0
	v_mov_b32_e32 v53, 0
	v_mov_b32_e32 v54, 0
	v_mov_b32_e32 v55, 0
	v_mov_b32_e32 v56, 0
	v_mov_b32_e32 v57, 0
	v_mov_b32_e32 v58, 0
	v_mov_b32_e32 v59, 0
	v_mov_b32_e32 v60, 0
	v_mov_b32_e32 v61, 0
	v_mov_b32_e32 v62, 0
	v_mov_b32_e32 v63, 0
	v_mov_b32_e32 v64, 0
	v_mov_b32_e32 v65, 0
	v_mov_b32_e32 v66, 0
	v_mov_b32_e32 v67, 0
	v_mov_b32_e32 v68, 0
	v_mov_b32_e32 v69, 0
	v_mov_b32_e32 v70, 0
	v_mov_b32_e32 v71, 0
	v_mov_b32_e32 v72, 0
	v_mov_b32_e32 v73, 0
	v_mov_b32_e32 v74, 0
	v_mov_b32_e32 v75, 0
	v_mov_b32_e32 v76, 0
	v_mov_b32_e32 v77, 0
	v_mov_b32_e32 v226, 0
	v_mov_b32_e32 v227, 0
	v_mov_b32_e32 v228, 0
	v_mov_b32_e32 v229, 0
	v_mov_b32_e32 v2, 0
	v_mov_b32_e32 v3, 0
	v_mov_b32_e32 v4, 0
	v_mov_b32_e32 v5, 0
	v_mov_b32_e32 v6, 0
	v_mov_b32_e32 v7, 0
	v_mov_b32_e32 v8, 0
	v_mov_b32_e32 v9, 0
	v_mul_u32_u24_e32 v199, 0x120, v223
	v_add3_u32 v199, v199, v194, s55
	v_mul_u32_u24_e32 v142, 0x210, v202
	v_lshl_add_u32 v142, v223, 4, v142
	v_add_u32_e32 v142, s55, v142
	v_lshrrev_b32_e32 v143, 2, v202
	v_lshl_add_u32 v143, v223, 3, v143
	v_mul_u32_u24_e32 v143, 0x120, v143
	v_and_b32_e32 v144, 3, v219
	v_lshl_add_u32 v143, v144, 3, v143
	v_add_u32_e32 v143, s55, v143
	ds_read2_b32 v[126:127], v191 offset0:64 offset1:68
	ds_read2_b32 v[128:129], v191 offset0:72 offset1:76
	ds_read2_b32 v[130:131], v191 offset0:80 offset1:84
	ds_read2_b32 v[132:133], v191 offset0:88 offset1:92
	s_waitcnt vmcnt(8)
	ds_write_b128 v199, v[18:21] offset:0
	ds_write_b128 v199, v[22:25] offset:1152
	ds_write_b128 v199, v[26:29] offset:2304
	ds_write_b128 v199, v[30:33] offset:3456
	ds_write_b128 v199, v[34:37] offset:4608
	ds_write_b128 v199, v[38:41] offset:5760
	ds_write_b128 v199, v[42:45] offset:6912
	ds_write_b128 v199, v[46:49] offset:8064
	s_waitcnt lgkmcnt(8)
	v_lshl_add_u32 v126, v126, 8, v194
	v_lshl_add_u32 v127, v127, 8, v194
	v_lshl_add_u32 v128, v128, 8, v194
	v_lshl_add_u32 v129, v129, 8, v194
	v_lshl_add_u32 v130, v130, 8, v194
	v_lshl_add_u32 v131, v131, 8, v194
	v_lshl_add_u32 v132, v132, 8, v194
	v_lshl_add_u32 v133, v133, 8, v194
	global_load_dwordx4 v[18:21], v126, s[46:47]
	global_load_dwordx4 v[22:25], v127, s[46:47]
	global_load_dwordx4 v[26:29], v128, s[46:47]
	global_load_dwordx4 v[30:33], v129, s[46:47]
	global_load_dwordx4 v[34:37], v130, s[46:47]
	global_load_dwordx4 v[38:41], v131, s[46:47]
	global_load_dwordx4 v[42:45], v132, s[46:47]
	global_load_dwordx4 v[46:49], v133, s[46:47]
	s_mov_b64 exec, s[70:71]
	ds_read_b128 v[2:5], v142 offset:9216
	s_mov_b64 exec, -1
	ds_read_b64_tr_b16 v[10:11], v143 offset:0
	ds_read_b64_tr_b16 v[12:13], v143 offset:1152
	ds_read_b64_tr_b16 v[14:15], v143 offset:32
	ds_read_b64_tr_b16 v[16:17], v143 offset:1184
	ds_read_b64_tr_b16 v[134:135], v143 offset:64
	ds_read_b64_tr_b16 v[136:137], v143 offset:1216
	ds_read_b64_tr_b16 v[138:139], v143 offset:96
	ds_read_b64_tr_b16 v[140:141], v143 offset:1248
	s_waitcnt lgkmcnt(6)
	v_mfma_f32_16x16x32_bf16 v[50:53], v[2:5], v[10:13], v[50:53]
	s_waitcnt lgkmcnt(4)
	v_mfma_f32_16x16x32_bf16 v[54:57], v[2:5], v[14:17], v[54:57]
	s_waitcnt lgkmcnt(2)
	v_mfma_f32_16x16x32_bf16 v[58:61], v[2:5], v[134:137], v[58:61]
	s_waitcnt lgkmcnt(0)
	v_mfma_f32_16x16x32_bf16 v[62:65], v[2:5], v[138:141], v[62:65]
	s_mov_b64 exec, s[70:71]
	ds_read_b128 v[6:9], v142 offset:11328
	s_mov_b64 exec, -1
	ds_read_b64_tr_b16 v[10:11], v143 offset:128
	ds_read_b64_tr_b16 v[12:13], v143 offset:1280
	ds_read_b64_tr_b16 v[14:15], v143 offset:160
	ds_read_b64_tr_b16 v[16:17], v143 offset:1312
	ds_read_b64_tr_b16 v[134:135], v143 offset:192
	ds_read_b64_tr_b16 v[136:137], v143 offset:1344
	ds_read_b64_tr_b16 v[138:139], v143 offset:224
	ds_read_b64_tr_b16 v[140:141], v143 offset:1376
	s_waitcnt lgkmcnt(6)
	v_mfma_f32_16x16x32_bf16 v[66:69], v[6:9], v[10:13], v[66:69]
	s_waitcnt lgkmcnt(4)
	v_mfma_f32_16x16x32_bf16 v[70:73], v[6:9], v[14:17], v[70:73]
	s_waitcnt lgkmcnt(2)
	v_mfma_f32_16x16x32_bf16 v[74:77], v[6:9], v[134:137], v[74:77]
	s_waitcnt lgkmcnt(0)
	v_mfma_f32_16x16x32_bf16 v[226:229], v[6:9], v[138:141], v[226:229]
	ds_read2_b32 v[126:127], v191 offset0:96 offset1:100
	ds_read2_b32 v[128:129], v191 offset0:104 offset1:108
	ds_read2_b32 v[130:131], v191 offset0:112 offset1:116
	ds_read2_b32 v[132:133], v191 offset0:120 offset1:124
	s_waitcnt vmcnt(8)
	ds_write_b128 v199, v[94:97] offset:0
	ds_write_b128 v199, v[98:101] offset:1152
	ds_write_b128 v199, v[102:105] offset:2304
	ds_write_b128 v199, v[106:109] offset:3456
	ds_write_b128 v199, v[110:113] offset:4608
	ds_write_b128 v199, v[114:117] offset:5760
	ds_write_b128 v199, v[118:121] offset:6912
	ds_write_b128 v199, v[122:125] offset:8064
	s_waitcnt lgkmcnt(8)
	v_lshl_add_u32 v126, v126, 8, v194
	v_lshl_add_u32 v127, v127, 8, v194
	v_lshl_add_u32 v128, v128, 8, v194
	v_lshl_add_u32 v129, v129, 8, v194
	v_lshl_add_u32 v130, v130, 8, v194
	v_lshl_add_u32 v131, v131, 8, v194
	v_lshl_add_u32 v132, v132, 8, v194
	v_lshl_add_u32 v133, v133, 8, v194
	global_load_dwordx4 v[94:97], v126, s[46:47]
	global_load_dwordx4 v[98:101], v127, s[46:47]
	global_load_dwordx4 v[102:105], v128, s[46:47]
	global_load_dwordx4 v[106:109], v129, s[46:47]
	global_load_dwordx4 v[110:113], v130, s[46:47]
	global_load_dwordx4 v[114:117], v131, s[46:47]
	global_load_dwordx4 v[118:121], v132, s[46:47]
	global_load_dwordx4 v[122:125], v133, s[46:47]
	s_mov_b64 exec, s[70:71]
	ds_read_b128 v[2:5], v142 offset:9280
	s_mov_b64 exec, -1
	ds_read_b64_tr_b16 v[10:11], v143 offset:0
	ds_read_b64_tr_b16 v[12:13], v143 offset:1152
	ds_read_b64_tr_b16 v[14:15], v143 offset:32
	ds_read_b64_tr_b16 v[16:17], v143 offset:1184
	ds_read_b64_tr_b16 v[134:135], v143 offset:64
	ds_read_b64_tr_b16 v[136:137], v143 offset:1216
	ds_read_b64_tr_b16 v[138:139], v143 offset:96
	ds_read_b64_tr_b16 v[140:141], v143 offset:1248
	s_waitcnt lgkmcnt(6)
	v_mfma_f32_16x16x32_bf16 v[50:53], v[2:5], v[10:13], v[50:53]
	s_waitcnt lgkmcnt(4)
	v_mfma_f32_16x16x32_bf16 v[54:57], v[2:5], v[14:17], v[54:57]
	s_waitcnt lgkmcnt(2)
	v_mfma_f32_16x16x32_bf16 v[58:61], v[2:5], v[134:137], v[58:61]
	s_waitcnt lgkmcnt(0)
	v_mfma_f32_16x16x32_bf16 v[62:65], v[2:5], v[138:141], v[62:65]
	s_mov_b64 exec, s[70:71]
	ds_read_b128 v[6:9], v142 offset:11392
	s_mov_b64 exec, -1
	ds_read_b64_tr_b16 v[10:11], v143 offset:128
	ds_read_b64_tr_b16 v[12:13], v143 offset:1280
	ds_read_b64_tr_b16 v[14:15], v143 offset:160
	ds_read_b64_tr_b16 v[16:17], v143 offset:1312
	ds_read_b64_tr_b16 v[134:135], v143 offset:192
	ds_read_b64_tr_b16 v[136:137], v143 offset:1344
	ds_read_b64_tr_b16 v[138:139], v143 offset:224
	ds_read_b64_tr_b16 v[140:141], v143 offset:1376
	s_waitcnt lgkmcnt(6)
	v_mfma_f32_16x16x32_bf16 v[66:69], v[6:9], v[10:13], v[66:69]
	s_waitcnt lgkmcnt(4)
	v_mfma_f32_16x16x32_bf16 v[70:73], v[6:9], v[14:17], v[70:73]
	s_waitcnt lgkmcnt(2)
	v_mfma_f32_16x16x32_bf16 v[74:77], v[6:9], v[134:137], v[74:77]
	s_waitcnt lgkmcnt(0)
	v_mfma_f32_16x16x32_bf16 v[226:229], v[6:9], v[138:141], v[226:229]
	ds_read2_b32 v[126:127], v191 offset0:128 offset1:132
	ds_read2_b32 v[128:129], v191 offset0:136 offset1:140
	ds_read2_b32 v[130:131], v191 offset0:144 offset1:148
	ds_read2_b32 v[132:133], v191 offset0:152 offset1:156
	s_waitcnt vmcnt(8)
	ds_write_b128 v199, v[18:21] offset:0
	ds_write_b128 v199, v[22:25] offset:1152
	ds_write_b128 v199, v[26:29] offset:2304
	ds_write_b128 v199, v[30:33] offset:3456
	ds_write_b128 v199, v[34:37] offset:4608
	ds_write_b128 v199, v[38:41] offset:5760
	ds_write_b128 v199, v[42:45] offset:6912
	ds_write_b128 v199, v[46:49] offset:8064
	s_waitcnt lgkmcnt(8)
	v_lshl_add_u32 v126, v126, 8, v194
	v_lshl_add_u32 v127, v127, 8, v194
	v_lshl_add_u32 v128, v128, 8, v194
	v_lshl_add_u32 v129, v129, 8, v194
	v_lshl_add_u32 v130, v130, 8, v194
	v_lshl_add_u32 v131, v131, 8, v194
	v_lshl_add_u32 v132, v132, 8, v194
	v_lshl_add_u32 v133, v133, 8, v194
	global_load_dwordx4 v[18:21], v126, s[46:47]
	global_load_dwordx4 v[22:25], v127, s[46:47]
	global_load_dwordx4 v[26:29], v128, s[46:47]
	global_load_dwordx4 v[30:33], v129, s[46:47]
	global_load_dwordx4 v[34:37], v130, s[46:47]
	global_load_dwordx4 v[38:41], v131, s[46:47]
	global_load_dwordx4 v[42:45], v132, s[46:47]
	global_load_dwordx4 v[46:49], v133, s[46:47]
	s_mov_b64 exec, s[70:71]
	ds_read_b128 v[2:5], v142 offset:9344
	s_mov_b64 exec, -1
	ds_read_b64_tr_b16 v[10:11], v143 offset:0
	ds_read_b64_tr_b16 v[12:13], v143 offset:1152
	ds_read_b64_tr_b16 v[14:15], v143 offset:32
	ds_read_b64_tr_b16 v[16:17], v143 offset:1184
	ds_read_b64_tr_b16 v[134:135], v143 offset:64
	ds_read_b64_tr_b16 v[136:137], v143 offset:1216
	ds_read_b64_tr_b16 v[138:139], v143 offset:96
	ds_read_b64_tr_b16 v[140:141], v143 offset:1248
	s_waitcnt lgkmcnt(6)
	v_mfma_f32_16x16x32_bf16 v[50:53], v[2:5], v[10:13], v[50:53]
	s_waitcnt lgkmcnt(4)
	v_mfma_f32_16x16x32_bf16 v[54:57], v[2:5], v[14:17], v[54:57]
	s_waitcnt lgkmcnt(2)
	v_mfma_f32_16x16x32_bf16 v[58:61], v[2:5], v[134:137], v[58:61]
	s_waitcnt lgkmcnt(0)
	v_mfma_f32_16x16x32_bf16 v[62:65], v[2:5], v[138:141], v[62:65]
	s_mov_b64 exec, s[70:71]
	ds_read_b128 v[6:9], v142 offset:11456
	s_mov_b64 exec, -1
	ds_read_b64_tr_b16 v[10:11], v143 offset:128
	ds_read_b64_tr_b16 v[12:13], v143 offset:1280
	ds_read_b64_tr_b16 v[14:15], v143 offset:160
	ds_read_b64_tr_b16 v[16:17], v143 offset:1312
	ds_read_b64_tr_b16 v[134:135], v143 offset:192
	ds_read_b64_tr_b16 v[136:137], v143 offset:1344
	ds_read_b64_tr_b16 v[138:139], v143 offset:224
	ds_read_b64_tr_b16 v[140:141], v143 offset:1376
	s_waitcnt lgkmcnt(6)
	v_mfma_f32_16x16x32_bf16 v[66:69], v[6:9], v[10:13], v[66:69]
	s_waitcnt lgkmcnt(4)
	v_mfma_f32_16x16x32_bf16 v[70:73], v[6:9], v[14:17], v[70:73]
	s_waitcnt lgkmcnt(2)
	v_mfma_f32_16x16x32_bf16 v[74:77], v[6:9], v[134:137], v[74:77]
	s_waitcnt lgkmcnt(0)
	v_mfma_f32_16x16x32_bf16 v[226:229], v[6:9], v[138:141], v[226:229]
	ds_read2_b32 v[126:127], v191 offset0:160 offset1:164
	ds_read2_b32 v[128:129], v191 offset0:168 offset1:172
	ds_read2_b32 v[130:131], v191 offset0:176 offset1:180
	ds_read2_b32 v[132:133], v191 offset0:184 offset1:188
	s_waitcnt vmcnt(8)
	ds_write_b128 v199, v[94:97] offset:0
	ds_write_b128 v199, v[98:101] offset:1152
	ds_write_b128 v199, v[102:105] offset:2304
	ds_write_b128 v199, v[106:109] offset:3456
	ds_write_b128 v199, v[110:113] offset:4608
	ds_write_b128 v199, v[114:117] offset:5760
	ds_write_b128 v199, v[118:121] offset:6912
	ds_write_b128 v199, v[122:125] offset:8064
	s_waitcnt lgkmcnt(8)
	v_lshl_add_u32 v126, v126, 8, v194
	v_lshl_add_u32 v127, v127, 8, v194
	v_lshl_add_u32 v128, v128, 8, v194
	v_lshl_add_u32 v129, v129, 8, v194
	v_lshl_add_u32 v130, v130, 8, v194
	v_lshl_add_u32 v131, v131, 8, v194
	v_lshl_add_u32 v132, v132, 8, v194
	v_lshl_add_u32 v133, v133, 8, v194
	global_load_dwordx4 v[94:97], v126, s[46:47]
	global_load_dwordx4 v[98:101], v127, s[46:47]
	global_load_dwordx4 v[102:105], v128, s[46:47]
	global_load_dwordx4 v[106:109], v129, s[46:47]
	global_load_dwordx4 v[110:113], v130, s[46:47]
	global_load_dwordx4 v[114:117], v131, s[46:47]
	global_load_dwordx4 v[118:121], v132, s[46:47]
	global_load_dwordx4 v[122:125], v133, s[46:47]
	s_mov_b64 exec, s[70:71]
	ds_read_b128 v[2:5], v142 offset:9408
	s_mov_b64 exec, -1
	ds_read_b64_tr_b16 v[10:11], v143 offset:0
	ds_read_b64_tr_b16 v[12:13], v143 offset:1152
	ds_read_b64_tr_b16 v[14:15], v143 offset:32
	ds_read_b64_tr_b16 v[16:17], v143 offset:1184
	ds_read_b64_tr_b16 v[134:135], v143 offset:64
	ds_read_b64_tr_b16 v[136:137], v143 offset:1216
	ds_read_b64_tr_b16 v[138:139], v143 offset:96
	ds_read_b64_tr_b16 v[140:141], v143 offset:1248
	s_waitcnt lgkmcnt(6)
	v_mfma_f32_16x16x32_bf16 v[50:53], v[2:5], v[10:13], v[50:53]
	s_waitcnt lgkmcnt(4)
	v_mfma_f32_16x16x32_bf16 v[54:57], v[2:5], v[14:17], v[54:57]
	s_waitcnt lgkmcnt(2)
	v_mfma_f32_16x16x32_bf16 v[58:61], v[2:5], v[134:137], v[58:61]
	s_waitcnt lgkmcnt(0)
	v_mfma_f32_16x16x32_bf16 v[62:65], v[2:5], v[138:141], v[62:65]
	s_mov_b64 exec, s[70:71]
	ds_read_b128 v[6:9], v142 offset:11520
	s_mov_b64 exec, -1
	ds_read_b64_tr_b16 v[10:11], v143 offset:128
	ds_read_b64_tr_b16 v[12:13], v143 offset:1280
	ds_read_b64_tr_b16 v[14:15], v143 offset:160
	ds_read_b64_tr_b16 v[16:17], v143 offset:1312
	ds_read_b64_tr_b16 v[134:135], v143 offset:192
	ds_read_b64_tr_b16 v[136:137], v143 offset:1344
	ds_read_b64_tr_b16 v[138:139], v143 offset:224
	ds_read_b64_tr_b16 v[140:141], v143 offset:1376
	s_waitcnt lgkmcnt(6)
	v_mfma_f32_16x16x32_bf16 v[66:69], v[6:9], v[10:13], v[66:69]
	s_waitcnt lgkmcnt(4)
	v_mfma_f32_16x16x32_bf16 v[70:73], v[6:9], v[14:17], v[70:73]
	s_waitcnt lgkmcnt(2)
	v_mfma_f32_16x16x32_bf16 v[74:77], v[6:9], v[134:137], v[74:77]
	s_waitcnt lgkmcnt(0)
	v_mfma_f32_16x16x32_bf16 v[226:229], v[6:9], v[138:141], v[226:229]
	ds_read2_b32 v[126:127], v191 offset0:192 offset1:196
	ds_read2_b32 v[128:129], v191 offset0:200 offset1:204
	ds_read2_b32 v[130:131], v191 offset0:208 offset1:212
	ds_read2_b32 v[132:133], v191 offset0:216 offset1:220
	s_waitcnt vmcnt(8)
	ds_write_b128 v199, v[18:21] offset:0
	ds_write_b128 v199, v[22:25] offset:1152
	ds_write_b128 v199, v[26:29] offset:2304
	ds_write_b128 v199, v[30:33] offset:3456
	ds_write_b128 v199, v[34:37] offset:4608
	ds_write_b128 v199, v[38:41] offset:5760
	ds_write_b128 v199, v[42:45] offset:6912
	ds_write_b128 v199, v[46:49] offset:8064
	s_waitcnt lgkmcnt(8)
	v_lshl_add_u32 v126, v126, 8, v194
	v_lshl_add_u32 v127, v127, 8, v194
	v_lshl_add_u32 v128, v128, 8, v194
	v_lshl_add_u32 v129, v129, 8, v194
	v_lshl_add_u32 v130, v130, 8, v194
	v_lshl_add_u32 v131, v131, 8, v194
	v_lshl_add_u32 v132, v132, 8, v194
	v_lshl_add_u32 v133, v133, 8, v194
	global_load_dwordx4 v[18:21], v126, s[46:47]
	global_load_dwordx4 v[22:25], v127, s[46:47]
	global_load_dwordx4 v[26:29], v128, s[46:47]
	global_load_dwordx4 v[30:33], v129, s[46:47]
	global_load_dwordx4 v[34:37], v130, s[46:47]
	global_load_dwordx4 v[38:41], v131, s[46:47]
	global_load_dwordx4 v[42:45], v132, s[46:47]
	global_load_dwordx4 v[46:49], v133, s[46:47]
	s_mov_b64 exec, s[70:71]
	ds_read_b128 v[2:5], v142 offset:9472
	s_mov_b64 exec, -1
	ds_read_b64_tr_b16 v[10:11], v143 offset:0
	ds_read_b64_tr_b16 v[12:13], v143 offset:1152
	ds_read_b64_tr_b16 v[14:15], v143 offset:32
	ds_read_b64_tr_b16 v[16:17], v143 offset:1184
	ds_read_b64_tr_b16 v[134:135], v143 offset:64
	ds_read_b64_tr_b16 v[136:137], v143 offset:1216
	ds_read_b64_tr_b16 v[138:139], v143 offset:96
	ds_read_b64_tr_b16 v[140:141], v143 offset:1248
	s_waitcnt lgkmcnt(6)
	v_mfma_f32_16x16x32_bf16 v[50:53], v[2:5], v[10:13], v[50:53]
	s_waitcnt lgkmcnt(4)
	v_mfma_f32_16x16x32_bf16 v[54:57], v[2:5], v[14:17], v[54:57]
	s_waitcnt lgkmcnt(2)
	v_mfma_f32_16x16x32_bf16 v[58:61], v[2:5], v[134:137], v[58:61]
	s_waitcnt lgkmcnt(0)
	v_mfma_f32_16x16x32_bf16 v[62:65], v[2:5], v[138:141], v[62:65]
	s_mov_b64 exec, s[70:71]
	ds_read_b128 v[6:9], v142 offset:11584
	s_mov_b64 exec, -1
	ds_read_b64_tr_b16 v[10:11], v143 offset:128
	ds_read_b64_tr_b16 v[12:13], v143 offset:1280
	ds_read_b64_tr_b16 v[14:15], v143 offset:160
	ds_read_b64_tr_b16 v[16:17], v143 offset:1312
	ds_read_b64_tr_b16 v[134:135], v143 offset:192
	ds_read_b64_tr_b16 v[136:137], v143 offset:1344
	ds_read_b64_tr_b16 v[138:139], v143 offset:224
	ds_read_b64_tr_b16 v[140:141], v143 offset:1376
	s_waitcnt lgkmcnt(6)
	v_mfma_f32_16x16x32_bf16 v[66:69], v[6:9], v[10:13], v[66:69]
	s_waitcnt lgkmcnt(4)
	v_mfma_f32_16x16x32_bf16 v[70:73], v[6:9], v[14:17], v[70:73]
	s_waitcnt lgkmcnt(2)
	v_mfma_f32_16x16x32_bf16 v[74:77], v[6:9], v[134:137], v[74:77]
	s_waitcnt lgkmcnt(0)
	v_mfma_f32_16x16x32_bf16 v[226:229], v[6:9], v[138:141], v[226:229]
	ds_read2_b32 v[126:127], v191 offset0:224 offset1:228
	ds_read2_b32 v[128:129], v191 offset0:232 offset1:236
	ds_read2_b32 v[130:131], v191 offset0:240 offset1:244
	ds_read2_b32 v[132:133], v191 offset0:248 offset1:252
	s_waitcnt vmcnt(8)
	ds_write_b128 v199, v[94:97] offset:0
	ds_write_b128 v199, v[98:101] offset:1152
	ds_write_b128 v199, v[102:105] offset:2304
	ds_write_b128 v199, v[106:109] offset:3456
	ds_write_b128 v199, v[110:113] offset:4608
	ds_write_b128 v199, v[114:117] offset:5760
	ds_write_b128 v199, v[118:121] offset:6912
	ds_write_b128 v199, v[122:125] offset:8064
	s_waitcnt lgkmcnt(8)
	v_lshl_add_u32 v126, v126, 8, v194
	v_lshl_add_u32 v127, v127, 8, v194
	v_lshl_add_u32 v128, v128, 8, v194
	v_lshl_add_u32 v129, v129, 8, v194
	v_lshl_add_u32 v130, v130, 8, v194
	v_lshl_add_u32 v131, v131, 8, v194
	v_lshl_add_u32 v132, v132, 8, v194
	v_lshl_add_u32 v133, v133, 8, v194
	global_load_dwordx4 v[94:97], v126, s[46:47]
	global_load_dwordx4 v[98:101], v127, s[46:47]
	global_load_dwordx4 v[102:105], v128, s[46:47]
	global_load_dwordx4 v[106:109], v129, s[46:47]
	global_load_dwordx4 v[110:113], v130, s[46:47]
	global_load_dwordx4 v[114:117], v131, s[46:47]
	global_load_dwordx4 v[118:121], v132, s[46:47]
	global_load_dwordx4 v[122:125], v133, s[46:47]
	s_mov_b64 exec, s[70:71]
	ds_read_b128 v[2:5], v142 offset:9536
	s_mov_b64 exec, -1
	ds_read_b64_tr_b16 v[10:11], v143 offset:0
	ds_read_b64_tr_b16 v[12:13], v143 offset:1152
	ds_read_b64_tr_b16 v[14:15], v143 offset:32
	ds_read_b64_tr_b16 v[16:17], v143 offset:1184
	ds_read_b64_tr_b16 v[134:135], v143 offset:64
	ds_read_b64_tr_b16 v[136:137], v143 offset:1216
	ds_read_b64_tr_b16 v[138:139], v143 offset:96
	ds_read_b64_tr_b16 v[140:141], v143 offset:1248
	s_waitcnt lgkmcnt(6)
	v_mfma_f32_16x16x32_bf16 v[50:53], v[2:5], v[10:13], v[50:53]
	s_waitcnt lgkmcnt(4)
	v_mfma_f32_16x16x32_bf16 v[54:57], v[2:5], v[14:17], v[54:57]
	s_waitcnt lgkmcnt(2)
	v_mfma_f32_16x16x32_bf16 v[58:61], v[2:5], v[134:137], v[58:61]
	s_waitcnt lgkmcnt(0)
	v_mfma_f32_16x16x32_bf16 v[62:65], v[2:5], v[138:141], v[62:65]
	s_mov_b64 exec, s[70:71]
	ds_read_b128 v[6:9], v142 offset:11648
	s_mov_b64 exec, -1
	ds_read_b64_tr_b16 v[10:11], v143 offset:128
	ds_read_b64_tr_b16 v[12:13], v143 offset:1280
	ds_read_b64_tr_b16 v[14:15], v143 offset:160
	ds_read_b64_tr_b16 v[16:17], v143 offset:1312
	ds_read_b64_tr_b16 v[134:135], v143 offset:192
	ds_read_b64_tr_b16 v[136:137], v143 offset:1344
	ds_read_b64_tr_b16 v[138:139], v143 offset:224
	ds_read_b64_tr_b16 v[140:141], v143 offset:1376
	s_waitcnt lgkmcnt(6)
	v_mfma_f32_16x16x32_bf16 v[66:69], v[6:9], v[10:13], v[66:69]
	s_waitcnt lgkmcnt(4)
	v_mfma_f32_16x16x32_bf16 v[70:73], v[6:9], v[14:17], v[70:73]
	s_waitcnt lgkmcnt(2)
	v_mfma_f32_16x16x32_bf16 v[74:77], v[6:9], v[134:137], v[74:77]
	s_waitcnt lgkmcnt(0)
	v_mfma_f32_16x16x32_bf16 v[226:229], v[6:9], v[138:141], v[226:229]
	s_waitcnt vmcnt(8)
	ds_write_b128 v199, v[18:21] offset:0
	ds_write_b128 v199, v[22:25] offset:1152
	ds_write_b128 v199, v[26:29] offset:2304
	ds_write_b128 v199, v[30:33] offset:3456
	ds_write_b128 v199, v[34:37] offset:4608
	ds_write_b128 v199, v[38:41] offset:5760
	ds_write_b128 v199, v[42:45] offset:6912
	ds_write_b128 v199, v[46:49] offset:8064
	s_mov_b64 exec, s[70:71]
	ds_read_b128 v[2:5], v142 offset:9600
	s_mov_b64 exec, -1
	ds_read_b64_tr_b16 v[10:11], v143 offset:0
	ds_read_b64_tr_b16 v[12:13], v143 offset:1152
	ds_read_b64_tr_b16 v[14:15], v143 offset:32
	ds_read_b64_tr_b16 v[16:17], v143 offset:1184
	ds_read_b64_tr_b16 v[134:135], v143 offset:64
	ds_read_b64_tr_b16 v[136:137], v143 offset:1216
	ds_read_b64_tr_b16 v[138:139], v143 offset:96
	ds_read_b64_tr_b16 v[140:141], v143 offset:1248
	s_waitcnt lgkmcnt(6)
	v_mfma_f32_16x16x32_bf16 v[50:53], v[2:5], v[10:13], v[50:53]
	s_waitcnt lgkmcnt(4)
	v_mfma_f32_16x16x32_bf16 v[54:57], v[2:5], v[14:17], v[54:57]
	s_waitcnt lgkmcnt(2)
	v_mfma_f32_16x16x32_bf16 v[58:61], v[2:5], v[134:137], v[58:61]
	s_waitcnt lgkmcnt(0)
	v_mfma_f32_16x16x32_bf16 v[62:65], v[2:5], v[138:141], v[62:65]
	s_mov_b64 exec, s[70:71]
	ds_read_b128 v[6:9], v142 offset:11712
	s_mov_b64 exec, -1
	ds_read_b64_tr_b16 v[10:11], v143 offset:128
	ds_read_b64_tr_b16 v[12:13], v143 offset:1280
	ds_read_b64_tr_b16 v[14:15], v143 offset:160
	ds_read_b64_tr_b16 v[16:17], v143 offset:1312
	ds_read_b64_tr_b16 v[134:135], v143 offset:192
	ds_read_b64_tr_b16 v[136:137], v143 offset:1344
	ds_read_b64_tr_b16 v[138:139], v143 offset:224
	ds_read_b64_tr_b16 v[140:141], v143 offset:1376
	s_waitcnt lgkmcnt(6)
	v_mfma_f32_16x16x32_bf16 v[66:69], v[6:9], v[10:13], v[66:69]
	s_waitcnt lgkmcnt(4)
	v_mfma_f32_16x16x32_bf16 v[70:73], v[6:9], v[14:17], v[70:73]
	s_waitcnt lgkmcnt(2)
	v_mfma_f32_16x16x32_bf16 v[74:77], v[6:9], v[134:137], v[74:77]
	s_waitcnt lgkmcnt(0)
	v_mfma_f32_16x16x32_bf16 v[226:229], v[6:9], v[138:141], v[226:229]
	s_waitcnt vmcnt(0)
	ds_write_b128 v199, v[94:97] offset:0
	ds_write_b128 v199, v[98:101] offset:1152
	ds_write_b128 v199, v[102:105] offset:2304
	ds_write_b128 v199, v[106:109] offset:3456
	ds_write_b128 v199, v[110:113] offset:4608
	ds_write_b128 v199, v[114:117] offset:5760
	ds_write_b128 v199, v[118:121] offset:6912
	ds_write_b128 v199, v[122:125] offset:8064
	s_mov_b64 exec, s[70:71]
	ds_read_b128 v[2:5], v142 offset:9664
	s_mov_b64 exec, -1
	ds_read_b64_tr_b16 v[10:11], v143 offset:0
	ds_read_b64_tr_b16 v[12:13], v143 offset:1152
	ds_read_b64_tr_b16 v[14:15], v143 offset:32
	ds_read_b64_tr_b16 v[16:17], v143 offset:1184
	ds_read_b64_tr_b16 v[134:135], v143 offset:64
	ds_read_b64_tr_b16 v[136:137], v143 offset:1216
	ds_read_b64_tr_b16 v[138:139], v143 offset:96
	ds_read_b64_tr_b16 v[140:141], v143 offset:1248
	s_waitcnt lgkmcnt(6)
	v_mfma_f32_16x16x32_bf16 v[50:53], v[2:5], v[10:13], v[50:53]
	s_waitcnt lgkmcnt(4)
	v_mfma_f32_16x16x32_bf16 v[54:57], v[2:5], v[14:17], v[54:57]
	s_waitcnt lgkmcnt(2)
	v_mfma_f32_16x16x32_bf16 v[58:61], v[2:5], v[134:137], v[58:61]
	s_waitcnt lgkmcnt(0)
	v_mfma_f32_16x16x32_bf16 v[62:65], v[2:5], v[138:141], v[62:65]
	s_mov_b64 exec, s[70:71]
	ds_read_b128 v[6:9], v142 offset:11776
	s_mov_b64 exec, -1
	ds_read_b64_tr_b16 v[10:11], v143 offset:128
	ds_read_b64_tr_b16 v[12:13], v143 offset:1280
	ds_read_b64_tr_b16 v[14:15], v143 offset:160
	ds_read_b64_tr_b16 v[16:17], v143 offset:1312
	ds_read_b64_tr_b16 v[134:135], v143 offset:192
	ds_read_b64_tr_b16 v[136:137], v143 offset:1344
	ds_read_b64_tr_b16 v[138:139], v143 offset:224
	ds_read_b64_tr_b16 v[140:141], v143 offset:1376
	s_waitcnt lgkmcnt(6)
	v_mfma_f32_16x16x32_bf16 v[66:69], v[6:9], v[10:13], v[66:69]
	s_waitcnt lgkmcnt(4)
	v_mfma_f32_16x16x32_bf16 v[70:73], v[6:9], v[14:17], v[70:73]
	s_waitcnt lgkmcnt(2)
	v_mfma_f32_16x16x32_bf16 v[74:77], v[6:9], v[134:137], v[74:77]
	s_waitcnt lgkmcnt(0)
	v_mfma_f32_16x16x32_bf16 v[226:229], v[6:9], v[138:141], v[226:229]
	s_nop 7
	s_nop 1
	v_lshl_add_u32 v144, v202, 1, s55
	s_mov_b64 exec, 0xffff
	v_mul_f32_e32 v50, s62, v50
	v_mul_f32_e32 v51, s63, v51
	v_mul_f32_e32 v52, s64, v52
	v_mul_f32_e32 v53, s65, v53
	v_cvt_pk_bf16_f32 v50, v50, v50
	v_cvt_pk_bf16_f32 v51, v51, v51
	v_cvt_pk_bf16_f32 v52, v52, v52
	v_cvt_pk_bf16_f32 v53, v53, v53
	ds_write_b16 v144, v50 offset:0
	ds_write_b16 v144, v51 offset:128
	ds_write_b16 v144, v52 offset:256
	ds_write_b16 v144, v53 offset:384
	v_mul_f32_e32 v54, s62, v54
	v_mul_f32_e32 v55, s63, v55
	v_mul_f32_e32 v56, s64, v56
	v_mul_f32_e32 v57, s65, v57
	v_cvt_pk_bf16_f32 v54, v54, v54
	v_cvt_pk_bf16_f32 v55, v55, v55
	v_cvt_pk_bf16_f32 v56, v56, v56
	v_cvt_pk_bf16_f32 v57, v57, v57
	ds_write_b16 v144, v54 offset:32
	ds_write_b16 v144, v55 offset:160
	ds_write_b16 v144, v56 offset:288
	ds_write_b16 v144, v57 offset:416
	v_mul_f32_e32 v58, s62, v58
	v_mul_f32_e32 v59, s63, v59
	v_mul_f32_e32 v60, s64, v60
	v_mul_f32_e32 v61, s65, v61
	v_cvt_pk_bf16_f32 v58, v58, v58
	v_cvt_pk_bf16_f32 v59, v59, v59
	v_cvt_pk_bf16_f32 v60, v60, v60
	v_cvt_pk_bf16_f32 v61, v61, v61
	ds_write_b16 v144, v58 offset:64
	ds_write_b16 v144, v59 offset:192
	ds_write_b16 v144, v60 offset:320
	ds_write_b16 v144, v61 offset:448
	v_mul_f32_e32 v62, s62, v62
	v_mul_f32_e32 v63, s63, v63
	v_mul_f32_e32 v64, s64, v64
	v_mul_f32_e32 v65, s65, v65
	v_cvt_pk_bf16_f32 v62, v62, v62
	v_cvt_pk_bf16_f32 v63, v63, v63
	v_cvt_pk_bf16_f32 v64, v64, v64
	v_cvt_pk_bf16_f32 v65, v65, v65
	ds_write_b16 v144, v62 offset:96
	ds_write_b16 v144, v63 offset:224
	ds_write_b16 v144, v64 offset:352
	ds_write_b16 v144, v65 offset:480
	v_mul_f32_e32 v66, s66, v66
	v_mul_f32_e32 v67, s67, v67
	v_mul_f32_e32 v68, s68, v68
	v_mul_f32_e32 v69, s69, v69
	v_cvt_pk_bf16_f32 v66, v66, v66
	v_cvt_pk_bf16_f32 v67, v67, v67
	v_cvt_pk_bf16_f32 v68, v68, v68
	v_cvt_pk_bf16_f32 v69, v69, v69
	ds_write_b16 v144, v66 offset:512
	ds_write_b16 v144, v67 offset:640
	ds_write_b16 v144, v68 offset:768
	ds_write_b16 v144, v69 offset:896
	v_mul_f32_e32 v70, s66, v70
	v_mul_f32_e32 v71, s67, v71
	v_mul_f32_e32 v72, s68, v72
	v_mul_f32_e32 v73, s69, v73
	v_cvt_pk_bf16_f32 v70, v70, v70
	v_cvt_pk_bf16_f32 v71, v71, v71
	v_cvt_pk_bf16_f32 v72, v72, v72
	v_cvt_pk_bf16_f32 v73, v73, v73
	ds_write_b16 v144, v70 offset:544
	ds_write_b16 v144, v71 offset:672
	ds_write_b16 v144, v72 offset:800
	ds_write_b16 v144, v73 offset:928
	v_mul_f32_e32 v74, s66, v74
	v_mul_f32_e32 v75, s67, v75
	v_mul_f32_e32 v76, s68, v76
	v_mul_f32_e32 v77, s69, v77
	v_cvt_pk_bf16_f32 v74, v74, v74
	v_cvt_pk_bf16_f32 v75, v75, v75
	v_cvt_pk_bf16_f32 v76, v76, v76
	v_cvt_pk_bf16_f32 v77, v77, v77
	ds_write_b16 v144, v74 offset:576
	ds_write_b16 v144, v75 offset:704
	ds_write_b16 v144, v76 offset:832
	ds_write_b16 v144, v77 offset:960
	v_mul_f32_e32 v226, s66, v226
	v_mul_f32_e32 v227, s67, v227
	v_mul_f32_e32 v228, s68, v228
	v_mul_f32_e32 v229, s69, v229
	v_cvt_pk_bf16_f32 v226, v226, v226
	v_cvt_pk_bf16_f32 v227, v227, v227
	v_cvt_pk_bf16_f32 v228, v228, v228
	v_cvt_pk_bf16_f32 v229, v229, v229
	ds_write_b16 v144, v226 offset:608
	ds_write_b16 v144, v227 offset:736
	ds_write_b16 v144, v228 offset:864
	ds_write_b16 v144, v229 offset:992
	s_mov_b64 exec, -1
	v_lshlrev_b32_e32 v142, 4, v219
	v_add_u32_e32 v143, s55, v142
	s_waitcnt lgkmcnt(0)
	ds_read_b128 v[10:13], v143
	s_waitcnt lgkmcnt(0)
	global_store_dwordx4 v142, v[10:13], s[50:51]
	s_mov_b64 s[0:1], exec
	s_branch .LBB0_317
.Lfa_skip:
	v_add_u32_e32 v38, v138, v237
	v_ashrrev_i32_e32 v131, 31, v130
	v_lshlrev_b64 v[34:35], 19, v[130:131]
	s_mov_b64 s[2:3], 0
	v_ashrrev_i32_e32 v39, 31, v38
	v_lshlrev_b32_e32 v0, 1, v216
	v_lshlrev_b32_e32 v36, 1, v214
	s_and_saveexec_b64 s[0:1], s[18:19]
	s_xor_b64 s[18:19], exec, s[0:1]
	s_cbranch_execz .LBB0_702
	v_readlane_b32 s36, v251, 1
	v_readlane_b32 s50, v251, 15
	v_readlane_b32 s51, v251, 16
	s_mov_b64 s[20:21], s[50:51]
	v_lshlrev_b64 v[224:225], 10, v[38:39]
	v_mov_b32_e32 v37, v1
	v_lshl_add_u64 v[18:19], s[20:21], 0, v[224:225]
	v_lshl_add_u64 v[18:19], v[18:19], 0, v[0:1]
	v_lshl_add_u64 v[18:19], v[18:19], 0, v[36:37]
	s_mov_b64 s[0:1], 0x6080000
	v_lshl_add_u64 v[36:37], v[18:19], 0, s[0:1]
	v_mov_b32_e32 v18, 0
	v_mov_b32_e32 v22, 0
	s_waitcnt lgkmcnt(0)
	v_mov_b32_e32 v23, 0
	v_mov_b32_e32 v24, 0
	v_mov_b32_e32 v25, 0
	v_readlane_b32 s37, v251, 2
	v_readlane_b32 s38, v251, 3
	v_readlane_b32 s39, v251, 4
	v_readlane_b32 s40, v251, 5
	v_readlane_b32 s41, v251, 6
	v_readlane_b32 s42, v251, 7
	v_readlane_b32 s43, v251, 8
	v_readlane_b32 s44, v251, 9
	v_readlane_b32 s45, v251, 10
	v_readlane_b32 s46, v251, 11
	v_readlane_b32 s47, v251, 12
	v_readlane_b32 s48, v251, 13
	v_readlane_b32 s49, v251, 14
	s_and_saveexec_b64 s[0:1], s[16:17]
	s_cbranch_execz .LBB0_686
	flat_load_dwordx4 v[22:25], v[36:37]
